# v7 + GEMM9 part 2: each row group's 16-byte exchange slot read with one coalesced dwordx4 sc1 load instead of four dword loads
# speedup vs baseline: 1.0336x; 1.0080x over previous
;     __device__ __forceinline__ void operator()(const f32x4 (&acc_)[2][2][4][2], const pg8::Unit& u, int wr, int wc, int fr, int fq) const {
;     ...
;         for (int bj = 0; bj < 2; ++bj) { g[bj][0] = *(const f32x4*)(gain + col0 + bj * 128); g[bj][1] = *(const f32x4*)(gain + col0 + bj * 128 + 4); }
; #pragma unroll
;         for (int ai = 0; ai < 2; ++ai)
; #pragma unroll
;             for (int m = 0; m < 4; ++m) {
;                 const int row = row0 + ai * 128 + m * 16; const float* xp = xch + (size_t)row * 16 + 4 * fq;
;                 float s = (__hip_atomic_load(xp + 0, __ATOMIC_RELAXED, __HIP_MEMORY_SCOPE_AGENT) + __hip_atomic_load(xp + 1, __ATOMIC_RELAXED, __HIP_MEMORY_SCOPE_AGENT))
;                         + (__hip_atomic_load(xp + 2, __ATOMIC_RELAXED, __HIP_MEMORY_SCOPE_AGENT) + __hip_atomic_load(xp + 3, __ATOMIC_RELAXED, __HIP_MEMORY_SCOPE_AGENT));
;                 s += __shfl_xor(s, 16); s += __shfl_xor(s, 32);
;                 const float rstd = __builtin_amdgcn_rsqf(s * (1.0f / 1024.0f) + EPS);
; #pragma unroll
;                 for (int bj = 0; bj < 2; ++bj) { const size_t off = (size_t)row * D + col0 + bj * 128;
;                     *(f32x4*)(out + off) = A[ai][bj][m][0] * rstd * g[bj][0]; *(f32x4*)(out + off + 4) = A[ai][bj][m][1] * rstd * g[bj][1]; }
;             }
.LBB0_982:
	v_lshlrev_b64 v[148:149], 2, v[148:149]
	s_waitcnt vmcnt(0)
	v_lshl_add_u64 v[8:9], s[24:25], 0, v[148:149]
	v_lshl_add_u64 v[156:157], v[136:137], 0, v[156:157]
	global_load_dwordx4 v[4:7], v[8:9], off offset:16
	global_load_dwordx4 v[12:15], v[8:9], off
	global_load_dwordx4 v[0:3], v[8:9], off offset:528
	s_nop 0
	global_load_dwordx4 v[8:11], v[8:9], off offset:512
	s_nop 0
	global_load_dwordx4 v[208:211], v[156:157], off sc1
	v_lshlrev_b64 v[146:147], 12, v[146:147]
	v_lshl_add_u64 v[146:147], s[8:9], 0, v[146:147]
	v_lshl_add_u64 v[146:147], v[146:147], 0, v[148:149]
	v_lshl_add_u64 v[160:161], v[136:137], 0, v[160:161]
	global_load_dwordx4 v[214:217], v[160:161], off sc1
	v_lshl_add_u64 v[242:243], v[136:137], 0, v[164:165]
	global_load_dwordx4 v[218:221], v[242:243], off sc1
	v_lshl_add_u64 v[244:245], v[136:137], 0, v[168:169]
	global_load_dwordx4 v[222:225], v[244:245], off sc1
	v_lshl_add_u64 v[242:243], v[136:137], 0, v[186:187]
	global_load_dwordx4 v[226:229], v[242:243], off sc1
	v_lshl_add_u64 v[244:245], v[136:137], 0, v[190:191]
	global_load_dwordx4 v[230:233], v[244:245], off sc1
	v_lshl_add_u64 v[242:243], v[136:137], 0, v[192:193]
	global_load_dwordx4 v[234:237], v[242:243], off sc1
	v_lshl_add_u64 v[244:245], v[136:137], 0, v[194:195]
	global_load_dwordx4 v[238:241], v[244:245], off sc1
	s_and_b64 vcc, exec, s[4:5]
	s_mov_b64 s[4:5], -1
	s_waitcnt vmcnt(0)
	v_add_f32_e32 v156, v208, v209
	v_add_f32_e32 v157, v210, v211
	s_nop 0
	v_add_f32_e32 v156, v156, v157
	ds_bpermute_b32 v157, v205, v156
	s_waitcnt lgkmcnt(0)
	v_add_f32_e32 v156, v156, v157
	ds_bpermute_b32 v157, v206, v156
	s_waitcnt lgkmcnt(0)
	v_add_f32_e32 v156, v156, v157
	v_fmamk_f32 v156, v156, 0x3a800000, v204
	v_rsq_f32_e32 v156, v156
	s_nop 0
	v_pk_mul_f32 v[124:125], v[124:125], v[156:157] op_sel_hi:[1,0]
	v_pk_mul_f32 v[126:127], v[126:127], v[156:157] op_sel_hi:[1,0]
	v_pk_mul_f32 v[120:121], v[120:121], v[156:157] op_sel_hi:[1,0]
	v_pk_mul_f32 v[122:123], v[122:123], v[156:157] op_sel_hi:[1,0]
	v_pk_mul_f32 v[208:209], v[116:117], v[156:157] op_sel_hi:[1,0]
	v_pk_mul_f32 v[210:211], v[118:119], v[156:157] op_sel_hi:[1,0]
	v_pk_mul_f32 v[212:213], v[112:113], v[156:157] op_sel_hi:[1,0]
	v_pk_mul_f32 v[156:157], v[114:115], v[156:157] op_sel_hi:[1,0]
	v_pk_mul_f32 v[114:115], v[14:15], v[126:127]
	v_pk_mul_f32 v[112:113], v[12:13], v[124:125]
	v_pk_mul_f32 v[118:119], v[6:7], v[122:123]
	v_pk_mul_f32 v[116:117], v[4:5], v[120:121]
	v_pk_mul_f32 v[122:123], v[10:11], v[210:211]
	v_pk_mul_f32 v[120:121], v[8:9], v[208:209]
	v_pk_mul_f32 v[126:127], v[2:3], v[156:157]
	v_pk_mul_f32 v[124:125], v[0:1], v[212:213]
	global_store_dwordx4 v[146:147], v[112:115], off
	global_store_dwordx4 v[146:147], v[116:119], off offset:16
	global_store_dwordx4 v[146:147], v[120:123], off offset:512
	global_store_dwordx4 v[146:147], v[124:127], off offset:528
	v_add_f32_e32 v112, v214, v215
	v_add_f32_e32 v113, v216, v217
	s_nop 0
	v_add_f32_e32 v112, v112, v113
	ds_bpermute_b32 v113, v205, v112
	s_waitcnt lgkmcnt(0)
	v_add_f32_e32 v114, v112, v113
	ds_bpermute_b32 v115, v206, v114
	v_lshlrev_b64 v[112:113], 12, v[150:151]
	v_lshl_add_u64 v[112:113], s[8:9], 0, v[112:113]
	v_lshl_add_u64 v[112:113], v[112:113], 0, v[148:149]
	s_waitcnt lgkmcnt(0)
	v_add_f32_e32 v114, v114, v115
	v_fmamk_f32 v114, v114, 0x3a800000, v204
	v_rsq_f32_e32 v114, v114
	s_nop 0
	v_pk_mul_f32 v[108:109], v[108:109], v[114:115] op_sel_hi:[1,0]
	v_pk_mul_f32 v[110:111], v[110:111], v[114:115] op_sel_hi:[1,0]
	v_pk_mul_f32 v[104:105], v[104:105], v[114:115] op_sel_hi:[1,0]
	v_pk_mul_f32 v[106:107], v[106:107], v[114:115] op_sel_hi:[1,0]
	v_pk_mul_f32 v[118:119], v[100:101], v[114:115] op_sel_hi:[1,0]
	v_pk_mul_f32 v[120:121], v[102:103], v[114:115] op_sel_hi:[1,0]
	v_pk_mul_f32 v[122:123], v[96:97], v[114:115] op_sel_hi:[1,0]
	v_pk_mul_f32 v[114:115], v[98:99], v[114:115] op_sel_hi:[1,0]
	v_pk_mul_f32 v[98:99], v[14:15], v[110:111]
	v_pk_mul_f32 v[96:97], v[12:13], v[108:109]
	v_pk_mul_f32 v[102:103], v[6:7], v[106:107]
	v_pk_mul_f32 v[100:101], v[4:5], v[104:105]
	v_pk_mul_f32 v[106:107], v[10:11], v[120:121]
	v_pk_mul_f32 v[104:105], v[8:9], v[118:119]
	v_pk_mul_f32 v[110:111], v[2:3], v[114:115]
	v_pk_mul_f32 v[108:109], v[0:1], v[122:123]
	global_store_dwordx4 v[112:113], v[96:99], off
	global_store_dwordx4 v[112:113], v[100:103], off offset:16
	global_store_dwordx4 v[112:113], v[104:107], off offset:512
	global_store_dwordx4 v[112:113], v[108:111], off offset:528
	v_add_f32_e32 v96, v218, v219
	v_add_f32_e32 v97, v220, v221
	s_nop 0
	v_add_f32_e32 v96, v96, v97
	ds_bpermute_b32 v97, v205, v96
	s_waitcnt lgkmcnt(0)
	v_add_f32_e32 v98, v96, v97
	ds_bpermute_b32 v99, v206, v98
	v_lshlrev_b64 v[96:97], 12, v[152:153]
	v_lshl_add_u64 v[96:97], s[8:9], 0, v[96:97]
	v_lshl_add_u64 v[96:97], v[96:97], 0, v[148:149]
	s_waitcnt lgkmcnt(0)
	v_add_f32_e32 v98, v98, v99
	v_fmamk_f32 v98, v98, 0x3a800000, v204
	v_rsq_f32_e32 v98, v98
	s_nop 0
	v_pk_mul_f32 v[92:93], v[92:93], v[98:99] op_sel_hi:[1,0]
	v_pk_mul_f32 v[94:95], v[94:95], v[98:99] op_sel_hi:[1,0]
	v_pk_mul_f32 v[88:89], v[88:89], v[98:99] op_sel_hi:[1,0]
	v_pk_mul_f32 v[90:91], v[90:91], v[98:99] op_sel_hi:[1,0]
	v_pk_mul_f32 v[102:103], v[84:85], v[98:99] op_sel_hi:[1,0]
	v_pk_mul_f32 v[104:105], v[86:87], v[98:99] op_sel_hi:[1,0]
	v_pk_mul_f32 v[106:107], v[80:81], v[98:99] op_sel_hi:[1,0]
	v_pk_mul_f32 v[98:99], v[82:83], v[98:99] op_sel_hi:[1,0]
	v_pk_mul_f32 v[82:83], v[14:15], v[94:95]
	v_pk_mul_f32 v[80:81], v[12:13], v[92:93]
	v_pk_mul_f32 v[86:87], v[6:7], v[90:91]
	v_pk_mul_f32 v[84:85], v[4:5], v[88:89]
	v_pk_mul_f32 v[90:91], v[10:11], v[104:105]
	v_pk_mul_f32 v[88:89], v[8:9], v[102:103]
	v_pk_mul_f32 v[94:95], v[2:3], v[98:99]
	v_pk_mul_f32 v[92:93], v[0:1], v[106:107]
	global_store_dwordx4 v[96:97], v[80:83], off
	global_store_dwordx4 v[96:97], v[84:87], off offset:16
	global_store_dwordx4 v[96:97], v[88:91], off offset:512
	global_store_dwordx4 v[96:97], v[92:95], off offset:528
	v_add_f32_e32 v80, v222, v223
	v_add_f32_e32 v81, v224, v225
	s_nop 0
	v_add_f32_e32 v80, v80, v81
	ds_bpermute_b32 v81, v205, v80
	s_waitcnt lgkmcnt(0)
;     __device__ __forceinline__ void operator()(const f32x4 (&acc_)[2][2][4][2], const pg8::Unit& u, int wr, int wc, int fr, int fq) const {
;     ...
;             for (int m = 0; m < 4; ++m) {
;                 const int row = row0 + ai * 128 + m * 16; const float* xp = xch + (size_t)row * 16 + 4 * fq;
;                 float s = (__hip_atomic_load(xp + 0, __ATOMIC_RELAXED, __HIP_MEMORY_SCOPE_AGENT) + __hip_atomic_load(xp + 1, __ATOMIC_RELAXED, __HIP_MEMORY_SCOPE_AGENT))
;                         + (__hip_atomic_load(xp + 2, __ATOMIC_RELAXED, __HIP_MEMORY_SCOPE_AGENT) + __hip_atomic_load(xp + 3, __ATOMIC_RELAXED, __HIP_MEMORY_SCOPE_AGENT));
;                 s += __shfl_xor(s, 16); s += __shfl_xor(s, 32);
;                 const float rstd = __builtin_amdgcn_rsqf(s * (1.0f / 1024.0f) + EPS);
; #pragma unroll
;                 for (int bj = 0; bj < 2; ++bj) { const size_t off = (size_t)row * D + col0 + bj * 128;
;                     *(f32x4*)(out + off) = A[ai][bj][m][0] * rstd * g[bj][0]; *(f32x4*)(out + off + 4) = A[ai][bj][m][1] * rstd * g[bj][1]; }
;             }
	v_add_f32_e32 v82, v80, v81
	ds_bpermute_b32 v83, v206, v82
	v_lshlrev_b64 v[80:81], 12, v[154:155]
	v_lshl_add_u64 v[80:81], s[8:9], 0, v[80:81]
	v_lshl_add_u64 v[80:81], v[80:81], 0, v[148:149]
	s_waitcnt lgkmcnt(0)
	v_add_f32_e32 v82, v82, v83
	v_fmamk_f32 v82, v82, 0x3a800000, v204
	v_rsq_f32_e32 v82, v82
	s_nop 0
	v_pk_mul_f32 v[76:77], v[76:77], v[82:83] op_sel_hi:[1,0]
	v_pk_mul_f32 v[78:79], v[78:79], v[82:83] op_sel_hi:[1,0]
	v_pk_mul_f32 v[72:73], v[72:73], v[82:83] op_sel_hi:[1,0]
	v_pk_mul_f32 v[74:75], v[74:75], v[82:83] op_sel_hi:[1,0]
	v_pk_mul_f32 v[86:87], v[68:69], v[82:83] op_sel_hi:[1,0]
	v_pk_mul_f32 v[88:89], v[70:71], v[82:83] op_sel_hi:[1,0]
	v_pk_mul_f32 v[90:91], v[64:65], v[82:83] op_sel_hi:[1,0]
	v_pk_mul_f32 v[82:83], v[66:67], v[82:83] op_sel_hi:[1,0]
	v_pk_mul_f32 v[66:67], v[14:15], v[78:79]
	v_pk_mul_f32 v[64:65], v[12:13], v[76:77]
	v_pk_mul_f32 v[70:71], v[6:7], v[74:75]
	v_pk_mul_f32 v[68:69], v[4:5], v[72:73]
	v_pk_mul_f32 v[74:75], v[10:11], v[88:89]
	v_pk_mul_f32 v[72:73], v[8:9], v[86:87]
	v_pk_mul_f32 v[78:79], v[2:3], v[82:83]
	v_pk_mul_f32 v[76:77], v[0:1], v[90:91]
	global_store_dwordx4 v[80:81], v[64:67], off
	global_store_dwordx4 v[80:81], v[68:71], off offset:16
	global_store_dwordx4 v[80:81], v[72:75], off offset:512
	global_store_dwordx4 v[80:81], v[76:79], off offset:528
	v_add_f32_e32 v64, v226, v227
	v_add_f32_e32 v65, v228, v229
	s_nop 0
	v_add_f32_e32 v64, v64, v65
	ds_bpermute_b32 v65, v205, v64
	s_waitcnt lgkmcnt(0)
	v_add_f32_e32 v66, v64, v65
	ds_bpermute_b32 v67, v206, v66
	v_lshlrev_b64 v[64:65], 12, v[158:159]
	v_lshl_add_u64 v[64:65], s[8:9], 0, v[64:65]
	v_lshl_add_u64 v[64:65], v[64:65], 0, v[148:149]
	s_waitcnt lgkmcnt(0)
	v_add_f32_e32 v66, v66, v67
	v_fmamk_f32 v66, v66, 0x3a800000, v204
	v_rsq_f32_e32 v66, v66
	s_nop 0
	v_pk_mul_f32 v[60:61], v[60:61], v[66:67] op_sel_hi:[1,0]
	v_pk_mul_f32 v[62:63], v[62:63], v[66:67] op_sel_hi:[1,0]
	v_pk_mul_f32 v[56:57], v[56:57], v[66:67] op_sel_hi:[1,0]
	v_pk_mul_f32 v[58:59], v[58:59], v[66:67] op_sel_hi:[1,0]
	v_pk_mul_f32 v[70:71], v[52:53], v[66:67] op_sel_hi:[1,0]
	v_pk_mul_f32 v[72:73], v[54:55], v[66:67] op_sel_hi:[1,0]
	v_pk_mul_f32 v[74:75], v[48:49], v[66:67] op_sel_hi:[1,0]
	v_pk_mul_f32 v[66:67], v[50:51], v[66:67] op_sel_hi:[1,0]
	v_pk_mul_f32 v[50:51], v[14:15], v[62:63]
	v_pk_mul_f32 v[48:49], v[12:13], v[60:61]
	v_pk_mul_f32 v[54:55], v[6:7], v[58:59]
	v_pk_mul_f32 v[52:53], v[4:5], v[56:57]
	v_pk_mul_f32 v[58:59], v[10:11], v[72:73]
	v_pk_mul_f32 v[56:57], v[8:9], v[70:71]
	v_pk_mul_f32 v[62:63], v[2:3], v[66:67]
	v_pk_mul_f32 v[60:61], v[0:1], v[74:75]
	global_store_dwordx4 v[64:65], v[48:51], off
	global_store_dwordx4 v[64:65], v[52:55], off offset:16
	global_store_dwordx4 v[64:65], v[56:59], off offset:512
	global_store_dwordx4 v[64:65], v[60:63], off offset:528
	v_add_f32_e32 v48, v230, v231
	v_add_f32_e32 v49, v232, v233
	s_nop 0
	v_add_f32_e32 v48, v48, v49
	ds_bpermute_b32 v49, v205, v48
	s_waitcnt lgkmcnt(0)
	v_add_f32_e32 v50, v48, v49
	ds_bpermute_b32 v51, v206, v50
	v_lshlrev_b64 v[48:49], 12, v[162:163]
	v_lshl_add_u64 v[48:49], s[8:9], 0, v[48:49]
	v_lshl_add_u64 v[48:49], v[48:49], 0, v[148:149]
	s_waitcnt lgkmcnt(0)
;     __device__ __forceinline__ void operator()(const f32x4 (&acc_)[2][2][4][2], const pg8::Unit& u, int wr, int wc, int fr, int fq) const {
;     ...
;             for (int m = 0; m < 4; ++m) {
;                 const int row = row0 + ai * 128 + m * 16; const float* xp = xch + (size_t)row * 16 + 4 * fq;
;                 float s = (__hip_atomic_load(xp + 0, __ATOMIC_RELAXED, __HIP_MEMORY_SCOPE_AGENT) + __hip_atomic_load(xp + 1, __ATOMIC_RELAXED, __HIP_MEMORY_SCOPE_AGENT))
;                         + (__hip_atomic_load(xp + 2, __ATOMIC_RELAXED, __HIP_MEMORY_SCOPE_AGENT) + __hip_atomic_load(xp + 3, __ATOMIC_RELAXED, __HIP_MEMORY_SCOPE_AGENT));
;                 s += __shfl_xor(s, 16); s += __shfl_xor(s, 32);
;                 const float rstd = __builtin_amdgcn_rsqf(s * (1.0f / 1024.0f) + EPS);
; #pragma unroll
;                 for (int bj = 0; bj < 2; ++bj) { const size_t off = (size_t)row * D + col0 + bj * 128;
;                     *(f32x4*)(out + off) = A[ai][bj][m][0] * rstd * g[bj][0]; *(f32x4*)(out + off + 4) = A[ai][bj][m][1] * rstd * g[bj][1]; }
;             }
	v_add_f32_e32 v50, v50, v51
	v_fmamk_f32 v50, v50, 0x3a800000, v204
	v_rsq_f32_e32 v50, v50
	s_nop 0
	v_pk_mul_f32 v[44:45], v[44:45], v[50:51] op_sel_hi:[1,0]
	v_pk_mul_f32 v[46:47], v[46:47], v[50:51] op_sel_hi:[1,0]
	v_pk_mul_f32 v[40:41], v[40:41], v[50:51] op_sel_hi:[1,0]
	v_pk_mul_f32 v[42:43], v[42:43], v[50:51] op_sel_hi:[1,0]
	v_pk_mul_f32 v[54:55], v[36:37], v[50:51] op_sel_hi:[1,0]
	v_pk_mul_f32 v[56:57], v[38:39], v[50:51] op_sel_hi:[1,0]
	v_pk_mul_f32 v[58:59], v[32:33], v[50:51] op_sel_hi:[1,0]
	v_pk_mul_f32 v[50:51], v[34:35], v[50:51] op_sel_hi:[1,0]
	v_pk_mul_f32 v[34:35], v[14:15], v[46:47]
	v_pk_mul_f32 v[32:33], v[12:13], v[44:45]
	v_pk_mul_f32 v[38:39], v[6:7], v[42:43]
	v_pk_mul_f32 v[36:37], v[4:5], v[40:41]
	v_pk_mul_f32 v[42:43], v[10:11], v[56:57]
	v_pk_mul_f32 v[40:41], v[8:9], v[54:55]
	v_pk_mul_f32 v[46:47], v[2:3], v[50:51]
	v_pk_mul_f32 v[44:45], v[0:1], v[58:59]
	global_store_dwordx4 v[48:49], v[32:35], off
	global_store_dwordx4 v[48:49], v[36:39], off offset:16
	global_store_dwordx4 v[48:49], v[40:43], off offset:512
	global_store_dwordx4 v[48:49], v[44:47], off offset:528
	v_add_f32_e32 v32, v234, v235
	v_add_f32_e32 v33, v236, v237
	s_nop 0
	v_add_f32_e32 v32, v32, v33
	ds_bpermute_b32 v33, v205, v32
	s_waitcnt lgkmcnt(0)
	v_add_f32_e32 v34, v32, v33
	ds_bpermute_b32 v35, v206, v34
	v_lshlrev_b64 v[32:33], 12, v[166:167]
	v_lshl_add_u64 v[32:33], s[8:9], 0, v[32:33]
	v_lshl_add_u64 v[32:33], v[32:33], 0, v[148:149]
	s_waitcnt lgkmcnt(0)
	v_add_f32_e32 v34, v34, v35
	v_fmamk_f32 v34, v34, 0x3a800000, v204
	v_rsq_f32_e32 v34, v34
	s_nop 0
	v_pk_mul_f32 v[28:29], v[28:29], v[34:35] op_sel_hi:[1,0]
	v_pk_mul_f32 v[30:31], v[30:31], v[34:35] op_sel_hi:[1,0]
	v_pk_mul_f32 v[24:25], v[24:25], v[34:35] op_sel_hi:[1,0]
	v_pk_mul_f32 v[26:27], v[26:27], v[34:35] op_sel_hi:[1,0]
	v_pk_mul_f32 v[38:39], v[20:21], v[34:35] op_sel_hi:[1,0]
	v_pk_mul_f32 v[40:41], v[22:23], v[34:35] op_sel_hi:[1,0]
	v_pk_mul_f32 v[42:43], v[16:17], v[34:35] op_sel_hi:[1,0]
	v_pk_mul_f32 v[34:35], v[18:19], v[34:35] op_sel_hi:[1,0]
	v_pk_mul_f32 v[18:19], v[14:15], v[30:31]
	v_pk_mul_f32 v[16:17], v[12:13], v[28:29]
	v_pk_mul_f32 v[22:23], v[6:7], v[26:27]
	v_pk_mul_f32 v[20:21], v[4:5], v[24:25]
	v_pk_mul_f32 v[26:27], v[10:11], v[40:41]
	v_pk_mul_f32 v[24:25], v[8:9], v[38:39]
	v_pk_mul_f32 v[30:31], v[2:3], v[34:35]
	v_pk_mul_f32 v[28:29], v[0:1], v[42:43]
	global_store_dwordx4 v[32:33], v[16:19], off
	global_store_dwordx4 v[32:33], v[20:23], off offset:16
	global_store_dwordx4 v[32:33], v[24:27], off offset:512
	global_store_dwordx4 v[32:33], v[28:31], off offset:528
	v_add_f32_e32 v16, v238, v239
	v_add_f32_e32 v17, v240, v241
	s_nop 0
	v_add_f32_e32 v16, v16, v17
	ds_bpermute_b32 v17, v205, v16
	s_waitcnt lgkmcnt(0)
	v_add_f32_e32 v18, v16, v17
	ds_bpermute_b32 v19, v206, v18
	v_lshlrev_b64 v[16:17], 12, v[170:171]
	v_lshl_add_u64 v[16:17], s[8:9], 0, v[16:17]
	v_lshl_add_u64 v[16:17], v[16:17], 0, v[148:149]
	s_waitcnt lgkmcnt(0)
	v_add_f32_e32 v18, v18, v19
	v_fmamk_f32 v18, v18, 0x3a800000, v204
	v_rsq_f32_e32 v18, v18
	s_nop 0
	v_pk_mul_f32 v[20:21], v[178:179], v[18:19] op_sel_hi:[1,0]
	v_pk_mul_f32 v[22:23], v[174:175], v[18:19] op_sel_hi:[1,0]
	v_pk_mul_f32 v[24:25], v[176:177], v[18:19] op_sel_hi:[1,0]
	v_pk_mul_f32 v[26:27], v[172:173], v[18:19] op_sel_hi:[1,0]
	v_pk_mul_f32 v[28:29], v[182:183], v[18:19] op_sel_hi:[1,0]
	v_pk_mul_f32 v[30:31], v[180:181], v[18:19] op_sel_hi:[1,0]
	v_pk_mul_f32 v[32:33], v[188:189], v[18:19] op_sel_hi:[1,0]
	v_pk_mul_f32 v[18:19], v[184:185], v[18:19] op_sel_hi:[1,0]
	v_pk_mul_f32 v[14:15], v[14:15], v[22:23]
	v_pk_mul_f32 v[12:13], v[12:13], v[20:21]
	v_pk_mul_f32 v[6:7], v[6:7], v[26:27]
	v_pk_mul_f32 v[4:5], v[4:5], v[24:25]
	v_pk_mul_f32 v[10:11], v[10:11], v[30:31]
	v_pk_mul_f32 v[8:9], v[8:9], v[28:29]
	v_pk_mul_f32 v[2:3], v[2:3], v[18:19]
	v_pk_mul_f32 v[0:1], v[0:1], v[32:33]
	global_store_dwordx4 v[16:17], v[12:15], off
	global_store_dwordx4 v[16:17], v[4:7], off offset:16
	global_store_dwordx4 v[16:17], v[8:11], off offset:512
	global_store_dwordx4 v[16:17], v[0:3], off offset:528
	s_cbranch_vccnz .LBB0_948
	s_andn2_b64 vcc, exec, s[22:23]
	s_cbranch_vccnz .LBB0_947
	s_barrier
	s_branch .LBB0_947
